# nt hint on the P0 filter-MLP (hid2) weight loads (read once per launch), on top of the current best
# baseline (speedup 1.0000x reference)
.LBB0_101:
	s_andn2_saveexec_b64 s[8:9], s[42:43]
	v_mul_f32_e32 v0, 0x39800801, v12
	s_or_b64 exec, exec, s[8:9]
	ds_write_b32 v17, v0 offset:512
	s_waitcnt lgkmcnt(0)
	global_load_dword v12, v[2:3], off nt
	s_mov_b64 s[8:9], 0
	v_mov_b32_e32 v0, v16
	s_waitcnt vmcnt(0)
	v_mov_b32_e32 v13, v12
.LBB0_104:
	v_lshl_add_u64 v[28:29], v[8:9], 0, s[8:9]
	global_load_dword v30, v[28:29], off nt
	global_load_dword v32, v[28:29], off offset:256 nt
	global_load_dword v36, v[28:29], off offset:512 nt
	global_load_dword v38, v[28:29], off offset:768 nt
	global_load_dword v40, v[28:29], off offset:1024 nt
	global_load_dword v42, v[28:29], off offset:1280 nt
	global_load_dword v44, v[28:29], off offset:1536 nt
	global_load_dword v46, v[28:29], off offset:1792 nt
	global_load_dword v48, v[28:29], off offset:2048 nt
	global_load_dword v50, v[28:29], off offset:2304 nt
	s_nop 0
	global_load_dword v28, v[28:29], off offset:2560 nt
	ds_read2_b32 v[52:53], v0 offset1:1
	ds_read2_b32 v[54:55], v0 offset0:2 offset1:3
	ds_read2_b32 v[56:57], v0 offset0:4 offset1:5
	ds_read2_b32 v[58:59], v0 offset0:6 offset1:7
	ds_read2_b32 v[60:61], v0 offset0:128 offset1:129
	ds_read2_b32 v[62:63], v0 offset0:130 offset1:131
	ds_read2_b32 v[64:65], v0 offset0:132 offset1:133
	ds_read2_b32 v[66:67], v0 offset0:8 offset1:9
	ds_read2_b32 v[68:69], v0 offset0:134 offset1:135
	ds_read2_b32 v[70:71], v0 offset0:136 offset1:137
	ds_read2_b32 v[72:73], v0 offset0:10 offset1:138
	s_waitcnt lgkmcnt(10)
	v_mov_b32_e32 v74, v52
	s_waitcnt lgkmcnt(6)
	v_mov_b32_e32 v75, v60
	v_mov_b32_e32 v60, v53
	v_mov_b32_e32 v52, v54
	s_waitcnt lgkmcnt(5)
	v_mov_b32_e32 v53, v62
	v_mov_b32_e32 v62, v55
	v_mov_b32_e32 v54, v56
	s_waitcnt lgkmcnt(4)
	v_mov_b32_e32 v55, v64
	v_mov_b32_e32 v64, v57
	v_mov_b32_e32 v56, v58
	s_waitcnt lgkmcnt(2)
	v_mov_b32_e32 v57, v68
	v_mov_b32_e32 v68, v59
	v_mov_b32_e32 v58, v66
	s_waitcnt lgkmcnt(1)
	v_mov_b32_e32 v59, v70
	s_add_u32 s8, s8, 0xb00
	v_mov_b32_e32 v70, v67
	s_addc_u32 s9, s9, 0
	v_add_u32_e32 v0, 44, v0
	s_cmpk_eq_i32 s8, 0x2100
	s_waitcnt vmcnt(10)
	v_pk_fma_f32 v[12:13], v[30:31], v[74:75], v[12:13] op_sel_hi:[0,1,1]
	s_waitcnt vmcnt(9)
	v_pk_fma_f32 v[12:13], v[32:33], v[60:61], v[12:13] op_sel_hi:[0,1,1]
	s_waitcnt vmcnt(8)
	v_pk_fma_f32 v[12:13], v[36:37], v[52:53], v[12:13] op_sel_hi:[0,1,1]
	s_waitcnt vmcnt(7)
	v_pk_fma_f32 v[12:13], v[38:39], v[62:63], v[12:13] op_sel_hi:[0,1,1]
	s_waitcnt vmcnt(6)
	v_pk_fma_f32 v[12:13], v[40:41], v[54:55], v[12:13] op_sel_hi:[0,1,1]
	s_waitcnt vmcnt(5)
	v_pk_fma_f32 v[12:13], v[42:43], v[64:65], v[12:13] op_sel_hi:[0,1,1]
	s_waitcnt vmcnt(4)
	v_pk_fma_f32 v[12:13], v[44:45], v[56:57], v[12:13] op_sel_hi:[0,1,1]
	s_waitcnt vmcnt(3)
	v_pk_fma_f32 v[12:13], v[46:47], v[68:69], v[12:13] op_sel_hi:[0,1,1]
	s_waitcnt vmcnt(2)
	v_pk_fma_f32 v[12:13], v[48:49], v[58:59], v[12:13] op_sel_hi:[0,1,1]
	s_waitcnt vmcnt(1)
	v_pk_fma_f32 v[12:13], v[50:51], v[70:71], v[12:13] op_sel_hi:[0,1,1]
	s_waitcnt vmcnt(0) lgkmcnt(0)
	v_pk_fma_f32 v[12:13], v[28:29], v[72:73], v[12:13] op_sel_hi:[0,1,1]
	s_cbranch_scc0 .LBB0_104
	global_load_dword v27, v[4:5], off nt
	s_waitcnt vmcnt(0)
	v_mul_f32_e32 v12, v12, v27
	v_and_b32_e32 v28, 0x7fffffff, v12
	v_cmp_nlt_f32_e64 s[8:9], |v12|, s33
	s_and_saveexec_b64 s[10:11], s[8:9]
	s_xor_b64 s[42:43], exec, s[10:11]
	s_cbranch_execz .LBB0_107
	v_lshrrev_b32_e32 v0, 23, v28
	v_add_u32_e32 v0, 0xffffff88, v0
	v_cmp_lt_u32_e64 s[8:9], 63, v0
	s_nop 1
	v_cndmask_b32_e64 v29, 0, v22, s[8:9]
	v_add_u32_e32 v0, v29, v0
	v_cmp_lt_u32_e64 s[10:11], 31, v0
	s_nop 1
	v_cndmask_b32_e64 v29, 0, v23, s[10:11]
	v_add_u32_e32 v0, v29, v0
	v_cmp_lt_u32_e64 s[12:13], 31, v0
	s_nop 1
	v_cndmask_b32_e64 v29, 0, v23, s[12:13]
	v_add_u32_e32 v29, v29, v0
	v_and_b32_e32 v0, 0x7fffff, v28
	v_or_b32_e32 v35, 0x800000, v0
	v_mad_u64_u32 v[30:31], s[14:15], v35, s68, 0
	v_mov_b32_e32 v0, v31
	v_mad_u64_u32 v[32:33], s[14:15], v35, s69, v[0:1]
	v_mov_b32_e32 v0, v33
	v_mad_u64_u32 v[36:37], s[14:15], v35, s82, v[0:1]
	v_mov_b32_e32 v0, v37
	v_mad_u64_u32 v[38:39], s[14:15], v35, s83, v[0:1]
	v_mov_b32_e32 v0, v39
	v_mad_u64_u32 v[40:41], s[14:15], v35, s84, v[0:1]
	v_mov_b32_e32 v0, v41
	v_mad_u64_u32 v[42:43], s[14:15], v35, s85, v[0:1]
	v_mov_b32_e32 v0, v43
	v_mad_u64_u32 v[44:45], s[14:15], v35, s86, v[0:1]
	v_cndmask_b32_e64 v31, v42, v38, s[8:9]
	v_cndmask_b32_e64 v0, v44, v40, s[8:9]
	v_cndmask_b32_e64 v35, v45, v42, s[8:9]
	v_cndmask_b32_e64 v33, v0, v31, s[10:11]
	v_cndmask_b32_e64 v0, v35, v0, s[10:11]
	v_cndmask_b32_e64 v35, v40, v36, s[8:9]
	v_cndmask_b32_e64 v31, v31, v35, s[10:11]
	v_sub_u32_e32 v37, 32, v29
	v_cmp_eq_u32_e64 s[14:15], 0, v29
	v_cndmask_b32_e64 v29, v38, v32, s[8:9]
	v_cndmask_b32_e64 v0, v0, v33, s[12:13]
	v_cndmask_b32_e64 v33, v33, v31, s[12:13]
	v_cndmask_b32_e64 v32, v35, v29, s[10:11]
	v_alignbit_b32 v39, v0, v33, v37
	v_cndmask_b32_e64 v31, v31, v32, s[12:13]
	v_cndmask_b32_e64 v0, v39, v0, s[14:15]
	v_alignbit_b32 v35, v33, v31, v37
	v_cndmask_b32_e64 v30, v36, v30, s[8:9]
	v_cndmask_b32_e64 v33, v35, v33, s[14:15]
	v_bfe_u32 v39, v0, 29, 1
	v_cndmask_b32_e64 v29, v29, v30, s[10:11]
	v_alignbit_b32 v35, v0, v33, 30
	v_sub_u32_e32 v40, 0, v39
	v_cndmask_b32_e64 v29, v32, v29, s[12:13]
	v_xor_b32_e32 v35, v35, v40
	v_alignbit_b32 v30, v31, v29, v37
	v_cndmask_b32_e64 v30, v30, v31, s[14:15]
	v_ffbh_u32_e32 v32, v35
	v_alignbit_b32 v31, v33, v30, 30
	v_min_u32_e32 v32, 32, v32
	v_alignbit_b32 v29, v30, v29, 30
	v_xor_b32_e32 v31, v31, v40
	v_sub_u32_e32 v33, 31, v32
	v_xor_b32_e32 v29, v29, v40
	v_alignbit_b32 v35, v35, v31, v33
	v_alignbit_b32 v29, v31, v29, v33
	v_alignbit_b32 v30, v35, v29, 9
	v_ffbh_u32_e32 v31, v30
	v_min_u32_e32 v31, 32, v31
	v_lshrrev_b32_e32 v38, 29, v0
	v_not_b32_e32 v33, v31
	v_alignbit_b32 v29, v30, v29, v33
	v_lshlrev_b32_e32 v30, 31, v38
	v_or_b32_e32 v33, 0x33000000, v30
	v_add_lshl_u32 v31, v31, v32, 23
	v_lshrrev_b32_e32 v29, 9, v29
	v_sub_u32_e32 v31, v33, v31
	v_or_b32_e32 v30, 0.5, v30
	v_lshlrev_b32_e32 v32, 23, v32
	v_or_b32_e32 v29, v31, v29
	v_lshrrev_b32_e32 v31, 9, v35
	v_sub_u32_e32 v30, v30, v32
	v_or_b32_e32 v30, v31, v30
	v_mul_f32_e32 v31, 0x3fc90fda, v30
	v_fma_f32 v32, v30, s87, -v31
	v_fmac_f32_e32 v32, 0x33a22168, v30
	v_fmac_f32_e32 v32, 0x3fc90fda, v29
	v_lshrrev_b32_e32 v0, 30, v0
	v_add_f32_e32 v29, v31, v32
	v_add_u32_e32 v0, v39, v0

.LBB0_111:
	s_andn2_saveexec_b64 s[8:9], s[42:43]
	v_mul_f32_e64 v0, |v12|, s88
	v_rndne_f32_e32 v29, v0
	v_cvt_i32_f32_e32 v0, v29
	v_fma_f32 v28, v29, s89, |v12|
	v_fmac_f32_e32 v28, 0xb3a22168, v29
	v_fmac_f32_e32 v28, 0xa7c234c4, v29
	s_or_b64 exec, exec, s[8:9]
	v_mul_f32_e32 v29, v28, v28
	v_fmamk_f32 v30, v29, 0xb94c1982, v20
	v_fmaak_f32 v30, v29, v30, 0xbe2aaa9d
	v_mul_f32_e32 v30, v29, v30
	v_fmac_f32_e32 v28, v28, v30
	v_fmamk_f32 v30, v29, 0x37d75334, v21
	v_fmaak_f32 v30, v29, v30, 0x3d2aabf7
	v_fmaak_f32 v30, v29, v30, 0xbf000004
	v_fma_f32 v29, v29, v30, 1.0
	v_and_b32_e32 v30, 1, v0
	v_lshlrev_b32_e32 v0, 30, v0
	v_cmp_eq_u32_e64 s[8:9], 0, v30
	v_and_b32_e32 v0, 0x80000000, v0
	v_xor_b32_e32 v13, v13, v12
	v_cndmask_b32_e64 v28, v29, v28, s[8:9]
	v_xor_b32_e32 v0, v13, v0
	v_xor_b32_e32 v0, v0, v28
	v_cmp_class_f32_e64 s[8:9], v12, s91
	s_nop 1
	v_cndmask_b32_e64 v0, v25, v0, s[8:9]
	ds_write_b32 v17, v0 offset:768
	s_waitcnt lgkmcnt(0)
	global_load_dword v12, v[6:7], off nt
	s_mov_b64 s[8:9], 0
	v_mov_b32_e32 v0, v19
	s_waitcnt vmcnt(0)
	v_mov_b32_e32 v13, v12
.LBB0_114:
	v_lshl_add_u64 v[28:29], v[10:11], 0, s[8:9]
	global_load_dword v32, v[28:29], off nt
	global_load_dword v64, v[28:29], off offset:256 nt
	global_load_dword v66, v[28:29], off offset:512 nt
	global_load_dword v68, v[28:29], off offset:768 nt
	global_load_dword v70, v[28:29], off offset:1024 nt
	global_load_dword v72, v[28:29], off offset:1280 nt
	global_load_dword v74, v[28:29], off offset:1536 nt
	global_load_dword v76, v[28:29], off offset:1792 nt
	global_load_dword v78, v[28:29], off offset:2048 nt
	global_load_dword v80, v[28:29], off offset:2304 nt
	global_load_dword v82, v[28:29], off offset:2560 nt
	global_load_dword v84, v[28:29], off offset:2816 nt
	global_load_dword v86, v[28:29], off offset:3072 nt
	global_load_dword v88, v[28:29], off offset:3328 nt
	global_load_dword v90, v[28:29], off offset:3584 nt
	global_load_dword v92, v[28:29], off offset:3840 nt
	ds_read_b128 v[28:31], v0
	ds_read_b128 v[36:39], v0 offset:16
	ds_read_b128 v[40:43], v0 offset:32
	ds_read_b128 v[44:47], v0 offset:48
	ds_read_b128 v[48:51], v0 offset:512
	ds_read_b128 v[52:55], v0 offset:528
	ds_read_b128 v[56:59], v0 offset:544
	ds_read_b128 v[60:63], v0 offset:560
	s_waitcnt lgkmcnt(7)
	v_mov_b32_e32 v95, v28
	s_waitcnt lgkmcnt(3)
	v_mov_b32_e32 v94, v48
	v_mov_b32_e32 v28, v49
	v_mov_b32_e32 v48, v50
	v_mov_b32_e32 v49, v30
	v_mov_b32_e32 v30, v51
	s_waitcnt lgkmcnt(2)
	v_mov_b32_e32 v50, v52
	v_mov_b32_e32 v51, v36
	v_mov_b32_e32 v36, v53
	v_mov_b32_e32 v52, v54
	v_mov_b32_e32 v53, v38
	v_mov_b32_e32 v38, v55
	s_waitcnt lgkmcnt(1)
	v_mov_b32_e32 v54, v56
	v_mov_b32_e32 v55, v40
	v_mov_b32_e32 v40, v57
	v_mov_b32_e32 v56, v58
	v_mov_b32_e32 v57, v42
	v_mov_b32_e32 v42, v59
	s_waitcnt lgkmcnt(0)
	v_mov_b32_e32 v58, v60
	v_mov_b32_e32 v59, v44
	v_mov_b32_e32 v44, v61
	s_add_u32 s8, s8, 0x1000
	v_mov_b32_e32 v60, v62
	v_mov_b32_e32 v61, v46
	s_addc_u32 s9, s9, 0
	v_mov_b32_e32 v46, v63
	v_add_u32_e32 v0, 64, v0
	s_cmpk_eq_i32 s8, 0x4000
	s_waitcnt vmcnt(15)
	v_pk_fma_f32 v[12:13], v[32:33], v[94:95], v[12:13] op_sel_hi:[0,1,1]
	s_waitcnt vmcnt(14)
	v_pk_fma_f32 v[12:13], v[64:65], v[28:29], v[12:13] op_sel_hi:[0,1,1]
	s_waitcnt vmcnt(13)
	v_pk_fma_f32 v[12:13], v[66:67], v[48:49], v[12:13] op_sel_hi:[0,1,1]
	s_waitcnt vmcnt(12)
	v_pk_fma_f32 v[12:13], v[68:69], v[30:31], v[12:13] op_sel_hi:[0,1,1]
	s_waitcnt vmcnt(11)
	v_pk_fma_f32 v[12:13], v[70:71], v[50:51], v[12:13] op_sel_hi:[0,1,1]
	s_waitcnt vmcnt(10)
	v_pk_fma_f32 v[12:13], v[72:73], v[36:37], v[12:13] op_sel_hi:[0,1,1]
	s_waitcnt vmcnt(9)
	v_pk_fma_f32 v[12:13], v[74:75], v[52:53], v[12:13] op_sel_hi:[0,1,1]
	s_waitcnt vmcnt(8)
	v_pk_fma_f32 v[12:13], v[76:77], v[38:39], v[12:13] op_sel_hi:[0,1,1]
	s_waitcnt vmcnt(7)
	v_pk_fma_f32 v[12:13], v[78:79], v[54:55], v[12:13] op_sel_hi:[0,1,1]
	s_waitcnt vmcnt(6)
	v_pk_fma_f32 v[12:13], v[80:81], v[40:41], v[12:13] op_sel_hi:[0,1,1]
	s_waitcnt vmcnt(5)
	v_pk_fma_f32 v[12:13], v[82:83], v[56:57], v[12:13] op_sel_hi:[0,1,1]
	s_waitcnt vmcnt(4)
	v_pk_fma_f32 v[12:13], v[84:85], v[42:43], v[12:13] op_sel_hi:[0,1,1]
	s_waitcnt vmcnt(3)
	v_pk_fma_f32 v[12:13], v[86:87], v[58:59], v[12:13] op_sel_hi:[0,1,1]
	s_waitcnt vmcnt(2)
	v_pk_fma_f32 v[12:13], v[88:89], v[44:45], v[12:13] op_sel_hi:[0,1,1]
	s_waitcnt vmcnt(1)
	v_pk_fma_f32 v[12:13], v[90:91], v[60:61], v[12:13] op_sel_hi:[0,1,1]
	s_waitcnt vmcnt(0)
	v_pk_fma_f32 v[12:13], v[92:93], v[46:47], v[12:13] op_sel_hi:[0,1,1]
	s_cbranch_scc0 .LBB0_114
	v_mul_f32_e32 v13, v27, v13
	v_and_b32_e32 v28, 0x7fffffff, v13
	v_cmp_nlt_f32_e64 s[8:9], |v13|, s33
	s_and_saveexec_b64 s[10:11], s[8:9]
	s_xor_b64 s[42:43], exec, s[10:11]
	s_cbranch_execz .LBB0_117
	v_lshrrev_b32_e32 v0, 23, v28
	v_add_u32_e32 v0, 0xffffff88, v0
	v_cmp_lt_u32_e64 s[8:9], 63, v0
	s_nop 1
	v_cndmask_b32_e64 v29, 0, v22, s[8:9]
	v_add_u32_e32 v0, v29, v0
	v_cmp_lt_u32_e64 s[10:11], 31, v0
	s_nop 1
	v_cndmask_b32_e64 v29, 0, v23, s[10:11]
	v_add_u32_e32 v0, v29, v0
	v_cmp_lt_u32_e64 s[12:13], 31, v0
	s_nop 1
	v_cndmask_b32_e64 v29, 0, v23, s[12:13]
	v_add_u32_e32 v29, v29, v0
	v_and_b32_e32 v0, 0x7fffff, v28
	v_or_b32_e32 v35, 0x800000, v0
	v_mad_u64_u32 v[30:31], s[14:15], v35, s68, 0
	v_mov_b32_e32 v0, v31
	v_mad_u64_u32 v[32:33], s[14:15], v35, s69, v[0:1]
	v_mov_b32_e32 v0, v33
	v_mad_u64_u32 v[36:37], s[14:15], v35, s82, v[0:1]
	v_mov_b32_e32 v0, v37
	v_mad_u64_u32 v[38:39], s[14:15], v35, s83, v[0:1]
	v_mov_b32_e32 v0, v39
	v_mad_u64_u32 v[40:41], s[14:15], v35, s84, v[0:1]
	v_mov_b32_e32 v0, v41
	v_mad_u64_u32 v[42:43], s[14:15], v35, s85, v[0:1]
	v_mov_b32_e32 v0, v43
	v_mad_u64_u32 v[44:45], s[14:15], v35, s86, v[0:1]
	v_cndmask_b32_e64 v31, v42, v38, s[8:9]
	v_cndmask_b32_e64 v0, v44, v40, s[8:9]
	v_cndmask_b32_e64 v35, v45, v42, s[8:9]
	v_cndmask_b32_e64 v33, v0, v31, s[10:11]
	v_cndmask_b32_e64 v0, v35, v0, s[10:11]
	v_cndmask_b32_e64 v35, v40, v36, s[8:9]
	v_cndmask_b32_e64 v31, v31, v35, s[10:11]
	v_sub_u32_e32 v37, 32, v29
	v_cmp_eq_u32_e64 s[14:15], 0, v29
	v_cndmask_b32_e64 v29, v38, v32, s[8:9]
	v_cndmask_b32_e64 v0, v0, v33, s[12:13]
	v_cndmask_b32_e64 v33, v33, v31, s[12:13]
	v_cndmask_b32_e64 v32, v35, v29, s[10:11]
	v_alignbit_b32 v39, v0, v33, v37
	v_cndmask_b32_e64 v31, v31, v32, s[12:13]
	v_cndmask_b32_e64 v0, v39, v0, s[14:15]
	v_alignbit_b32 v35, v33, v31, v37
	v_cndmask_b32_e64 v30, v36, v30, s[8:9]
	v_cndmask_b32_e64 v33, v35, v33, s[14:15]
	v_bfe_u32 v39, v0, 29, 1
	v_cndmask_b32_e64 v29, v29, v30, s[10:11]
	v_alignbit_b32 v35, v0, v33, 30
	v_sub_u32_e32 v40, 0, v39
	v_cndmask_b32_e64 v29, v32, v29, s[12:13]
	v_xor_b32_e32 v35, v35, v40
	v_alignbit_b32 v30, v31, v29, v37
	v_cndmask_b32_e64 v30, v30, v31, s[14:15]
	v_ffbh_u32_e32 v32, v35
	v_alignbit_b32 v31, v33, v30, 30
	v_min_u32_e32 v32, 32, v32
	v_alignbit_b32 v29, v30, v29, 30
	v_xor_b32_e32 v31, v31, v40
	v_sub_u32_e32 v33, 31, v32
	v_xor_b32_e32 v29, v29, v40
	v_alignbit_b32 v35, v35, v31, v33
	v_alignbit_b32 v29, v31, v29, v33
	v_alignbit_b32 v30, v35, v29, 9
	v_ffbh_u32_e32 v31, v30
	v_min_u32_e32 v31, 32, v31
	v_lshrrev_b32_e32 v38, 29, v0
	v_not_b32_e32 v33, v31
	v_alignbit_b32 v29, v30, v29, v33
	v_lshlrev_b32_e32 v30, 31, v38
	v_or_b32_e32 v33, 0x33000000, v30
	v_add_lshl_u32 v31, v31, v32, 23
	v_lshrrev_b32_e32 v29, 9, v29
	v_sub_u32_e32 v31, v33, v31
	v_or_b32_e32 v30, 0.5, v30
	v_lshlrev_b32_e32 v32, 23, v32
	v_or_b32_e32 v29, v31, v29
	v_lshrrev_b32_e32 v31, 9, v35
	v_sub_u32_e32 v30, v30, v32
	v_or_b32_e32 v30, v31, v30
	v_mul_f32_e32 v31, 0x3fc90fda, v30
	v_fma_f32 v32, v30, s87, -v31
	v_fmac_f32_e32 v32, 0x33a22168, v30
	v_fmac_f32_e32 v32, 0x3fc90fda, v29
	v_lshrrev_b32_e32 v0, 30, v0
	v_add_f32_e32 v29, v31, v32
	v_add_u32_e32 v0, v39, v0
